# FOX interior loop back-edge rotation: next iteration's two 64-bit DMA source addresses computed in the latch before the loop-back barrier
# baseline (speedup 1.0000x reference)
.LBB0_263:
	s_add_i32 s3, s37, -3
	s_lshl_b64 s[0:1], s[4:5], 1
	v_readlane_b32 s4, v255, 26
	v_readlane_b32 s5, v255, 27
	s_add_u32 s12, s4, s0
	s_addc_u32 s13, s5, s1
	s_lshl_b64 s[0:1], s[14:15], 1
	s_add_u32 s0, s4, s0
	s_addc_u32 s1, s5, s1
	v_lshl_add_u64 v[122:123], s[0:1], 0, v[112:113]
	s_cmp_ge_i32 s18, s3
	v_lshlrev_b32_e32 v139, 10, v127
	v_lshlrev_b32_e32 v140, 4, v126
	v_cmp_gt_u32_e64 s[40:41], 32, v128
	v_lshlrev_b32_e32 v141, 2, v128
	v_lshl_add_u32 v138, v126, 2, s2
	v_lshl_add_u32 v137, v133, 2, s2
	s_cbranch_scc1 .LBB0_275
	s_lshl_b32 s0, s18, 6
	s_or_b32 s1, s17, s0
	s_add_i32 s0, s0, 64
	v_add3_u32 v143, v142, s1, 64
	v_or_b32_e32 v124, s0, v128
	s_sub_i32 s2, 0, s16
	v_mov_b64_e32 v[220:221], s[12:13]
	s_movk_i32 s100, 0x1200
	v_mad_i64_i32 v[220:221], vcc, v124, s100, v[220:221]
	v_mad_i64_i32 v[222:223], vcc, v143, s100, v[122:123]
	s_mov_b64 s[100:101], 0x940
	v_lshl_add_u64 v[220:221], v[220:221], 0, s[100:101]
	s_mov_b64 s[100:101], 0xd40
	v_lshl_add_u64 v[222:223], v[222:223], 0, s[100:101]
	s_branch .LBB0_266
.LBB0_265:
	v_pk_add_f32 v[50:51], v[50:51], v[144:145]
	v_pk_add_f32 v[52:53], v[52:53], v[36:37]
	v_pk_add_f32 v[54:55], v[54:55], v[38:39]
	v_pk_add_f32 v[56:57], v[56:57], v[40:41]
	v_pk_add_f32 v[58:59], v[58:59], v[42:43]
	v_pk_add_f32 v[60:61], v[60:61], v[44:45]
	v_pk_add_f32 v[62:63], v[62:63], v[46:47]
	v_add_f32_e32 v32, v48, v112
	v_add_f32_e32 v33, v49, v125
	v_pk_add_f32 v[50:51], v[50:51], v[52:53]
	v_pk_add_f32 v[54:55], v[54:55], v[56:57]
	v_pk_add_f32 v[58:59], v[58:59], v[60:61]
	v_add_f32_e32 v32, v32, v33
	v_pk_add_f32 v[50:51], v[50:51], v[54:55]
	v_pk_add_f32 v[58:59], v[58:59], v[62:63]
	v_pk_add_f32 v[50:51], v[50:51], v[58:59]
	v_add_f32_e32 v32, v32, v50
	v_add_f32_e32 v32, v32, v51
	s_add_i32 s18, s18, 1
	v_add_f32_e32 v136, v136, v32
	v_add_u32_e32 v143, 64, v143
	v_add_u32_e32 v124, 64, v124
	v_mov_b64_e32 v[220:221], s[12:13]
	s_movk_i32 s100, 0x1200
	v_mad_i64_i32 v[220:221], vcc, v124, s100, v[220:221]
	v_mad_i64_i32 v[222:223], vcc, v143, s100, v[122:123]
	s_mov_b64 s[100:101], 0x940
	v_lshl_add_u64 v[220:221], v[220:221], 0, s[100:101]
	s_mov_b64 s[100:101], 0xd40
	v_lshl_add_u64 v[222:223], v[222:223], 0, s[100:101]
	s_and_b64 vcc, exec, s[38:39]
	s_cmp_ge_i32 s18, s3
	s_waitcnt vmcnt(0)
	s_waitcnt lgkmcnt(0)
	s_barrier
	s_cbranch_scc1 .LBB0_274
.LBB0_266:
	s_add_i32 s4, s2, s18
	s_and_b32 s4, s4, 1
	s_xor_b32 s4, s4, 1
	s_mulk_i32 s4, 0x5100
	s_add_i32 s4, s4, s36
	s_addk_i32 s4, 0x100
	s_mov_b32 m0, s4
	v_ashrrev_i32_e32 v125, 31, v124
	global_load_lds_dwordx4 v[220:221], off
	s_add_i32 m0, s4, 0x3000
	s_and_b64 vcc, exec, s[38:39]
	global_load_lds_dwordx4 v[222:223], off
	s_cbranch_vccnz .LBB0_268
	v_lshl_add_u64 v[32:33], v[124:125], 2, s[70:71]
	s_add_i32 m0, s4, 0x5000
	s_sub_i32 m0, m0, s36
	s_nop 0
	global_load_lds_dword v[32:33], off
